# lru deferred scan on sample tiles: the 4 initial-state loads issued together (one exposed latency instead of four)
# speedup vs baseline: 1.0008x; 1.0008x over previous
; template <int MODE> __device__ __forceinline__ void lru_phase(const Params& P, LAS unsigned char* lds, int l, int tid_in) {
;     ...
;         if (prev >= 0) {
;             const int pos0 = psamp ? 0 : ((pt0 + 16 * q) % LP);
;             const int rs = psamp ? -1 : (pos0 == 0 ? 0 : (LP - pos0 < 16 ? LP - pos0 : -1));
;             float hh = 0.f;
; #pragma unroll
;             for (int r = 0; r < 4; ++r) hh = fa[r * 128 + cs] * hh + fb[r * 128 + cs];
; #pragma unroll
;             for (int j = 0; j < 3; ++j) if (j < q) hh = pqa[j] * hh + pqb[j];
; #pragma unroll
;             for (int i = 0; i < 16; ++i) {
;                 const float a2 = psa[(16 * q + i) * 128 + cs], b2 = psb[(16 * q + i) * 128 + cs];
;                 const bool reset = psamp ? ((i & 3) == 0) : (i == rs);
;                 float h0 = 0.f; if (psamp && reset) h0 = P.in[I_SLRU][(size_t)(l * 128 + ((pt0 + 16 * q - NPT) >> 2) + (i >> 2)) * 1024 + cgs];
;                 hh = reset ? a2 * h0 + b2 : a2 * hh + b2;
;                 psb[(16 * q + i) * 128 + cs] = hh;
;             }
.LBB0_1204:
	ds_read_b32 v9, v207
	ds_read_b32 v4, v208
	ds_read_b32 v10, v209
	ds_read_b32 v5, v210
	ds_read_b32 v11, v211
	ds_read_b32 v7, v212
	ds_read_b32 v12, v213
	ds_read_b32 v8, v214
	v_lshl_add_u32 v6, v206, 2, s12
	ds_read2st64_b32 v[2:3], v6 offset0:68 offset1:196
	v_add_u32_e32 v0, s44, v191
	v_ashrrev_i32_e32 v0, 2, v0
	v_cndmask_b32_e64 v1, 0, 1, s[82:83]
	v_add_u32_e32 v0, s40, v0
	v_cmp_ne_u32_e64 s[54:55], 1, v1
	s_andn2_b64 vcc, exec, s[82:83]
	v_mov_b32_e32 v1, 0
	s_cbranch_vccnz .LBB0_1206
	v_ashrrev_i32_e32 v1, 31, v0
	v_lshlrev_b64 v[14:15], 12, v[0:1]
	v_lshl_add_u64 v[14:15], v[170:171], 0, v[14:15]
	global_load_dword v1, v[14:15], off
	v_or_b32_e32 v20, 1, v0
	v_ashrrev_i32_e32 v21, 31, v20
	v_lshlrev_b64 v[20:21], 12, v[20:21]
	v_lshl_add_u64 v[20:21], v[170:171], 0, v[20:21]
	global_load_dword v17, v[20:21], off
	v_or_b32_e32 v20, 2, v0
	v_ashrrev_i32_e32 v21, 31, v20
	v_lshlrev_b64 v[20:21], 12, v[20:21]
	v_lshl_add_u64 v[20:21], v[170:171], 0, v[20:21]
	global_load_dword v18, v[20:21], off
	v_or_b32_e32 v20, 3, v0
	v_ashrrev_i32_e32 v21, 31, v20
	v_lshlrev_b64 v[20:21], 12, v[20:21]
	v_lshl_add_u64 v[20:21], v[170:171], 0, v[20:21]
	global_load_dword v19, v[20:21], off
.LBB0_1206:
	s_waitcnt lgkmcnt(7)
	v_fmac_f32_e32 v4, 0, v9
	s_waitcnt lgkmcnt(5)
	v_fmac_f32_e32 v5, v4, v10
	s_waitcnt lgkmcnt(3)
	v_fmac_f32_e32 v7, v5, v11
	s_waitcnt lgkmcnt(1)
	v_fmac_f32_e32 v8, v7, v12
	v_fma_f32 v4, v172, v8, v157
	v_cndmask_b32_e64 v4, v8, v4, s[36:37]
	v_fma_f32 v5, v173, v4, v174
	v_cndmask_b32_e64 v4, v4, v5, s[30:31]
	v_fma_f32 v5, v156, v4, v175
	v_cndmask_b32_e64 v4, v4, v5, s[20:21]
	s_waitcnt vmcnt(0)
	v_cndmask_b32_e64 v1, v4, v1, s[0:1]
	ds_read2st64_b32 v[4:5], v6 offset0:70 offset1:72
	ds_read2st64_b32 v[8:9], v6 offset0:198 offset1:200
	s_waitcnt lgkmcnt(2)
	v_fmac_f32_e32 v3, v2, v1
	s_and_b64 vcc, exec, s[54:55]
	s_waitcnt lgkmcnt(0)
	v_fma_f32 v1, v4, v3, v8
	ds_write2st64_b32 v6, v3, v1 offset0:196 offset1:198
	v_fmac_f32_e32 v9, v5, v1
	ds_read2st64_b32 v[4:5], v6 offset0:74 offset1:76
	ds_read2st64_b32 v[2:3], v6 offset0:202 offset1:204
	s_waitcnt lgkmcnt(0)
	v_fma_f32 v1, v9, v4, v2
	ds_write2st64_b32 v6, v9, v1 offset0:200 offset1:202
	s_cbranch_vccnz .LBB0_1208
	v_mov_b32_e32 v1, v17
.LBB0_1208:
	s_waitcnt vmcnt(0)
	v_fmac_f32_e32 v3, v5, v1
	ds_read2st64_b32 v[4:5], v6 offset0:78 offset1:80
	ds_read2st64_b32 v[8:9], v6 offset0:206 offset1:208
	s_and_b64 vcc, exec, s[54:55]
	s_waitcnt lgkmcnt(0)
	v_fma_f32 v1, v4, v3, v8
	ds_write2st64_b32 v6, v3, v1 offset0:204 offset1:206
	v_fmac_f32_e32 v9, v1, v5
	ds_read2st64_b32 v[4:5], v6 offset0:82 offset1:84
	ds_read2st64_b32 v[2:3], v6 offset0:210 offset1:212
	s_waitcnt lgkmcnt(0)
	v_fma_f32 v1, v9, v4, v2
	ds_write2st64_b32 v6, v9, v1 offset0:208 offset1:210
	s_cbranch_vccnz .LBB0_1210
	v_mov_b32_e32 v1, v18
.LBB0_1210:
	s_waitcnt vmcnt(0)
	v_fmac_f32_e32 v3, v5, v1
	ds_read2st64_b32 v[4:5], v6 offset0:86 offset1:88
	ds_read2st64_b32 v[8:9], v6 offset0:214 offset1:216
	s_and_b64 vcc, exec, s[54:55]
	s_waitcnt lgkmcnt(0)
	v_fma_f32 v1, v4, v3, v8
	ds_write2st64_b32 v6, v3, v1 offset0:212 offset1:214
	v_fmac_f32_e32 v9, v1, v5
	ds_read2st64_b32 v[4:5], v6 offset0:90 offset1:92
	ds_read2st64_b32 v[2:3], v6 offset0:218 offset1:220
	s_waitcnt lgkmcnt(0)
	v_fma_f32 v1, v9, v4, v2
	ds_write2st64_b32 v6, v9, v1 offset0:216 offset1:218
	s_cbranch_vccnz .LBB0_1212
	v_mov_b32_e32 v1, v19
